# P0 item order: half of the workgroups walk their items backwards so compute-bound ssm_prep overlaps the memory-bound weight conversion of the other half
# baseline (speedup 1.0000x reference)
.Lp0rev_init:
	s_mov_b32 s100, s34
	s_mov_b32 s101, s22
	s_bitcmp1_b32 s0, 3
	s_cbranch_scc0 .Lp0rev_done
.Lp0rev_find:
	s_add_i32 s1, s90, s34
	s_cmpk_gt_i32 s1, 0x1aff
	s_cbranch_scc1 .Lp0rev_set
	s_mov_b32 s90, s1
	s_add_i32 s21, s21, s22
	s_branch .Lp0rev_find
.Lp0rev_set:
	s_sub_i32 s100, 0, s34
	s_sub_i32 s101, 0, s22

.LBB0_19:
	s_add_i32 s90, s90, s100
	s_add_i32 s21, s21, s101
	s_cmpk_gt_u32 s90, 0x1aff
	s_cbranch_scc1 .LBB0_84

	.amdhsa_kernel _Z4mega6Params
		.amdhsa_group_segment_fixed_size 148752
		.amdhsa_private_segment_fixed_size 0
		.amdhsa_kernarg_size 584
		.amdhsa_user_sgpr_count 2
		.amdhsa_user_sgpr_dispatch_ptr 0
		.amdhsa_user_sgpr_queue_ptr 0
		.amdhsa_user_sgpr_kernarg_segment_ptr 1
		.amdhsa_user_sgpr_dispatch_id 0
		.amdhsa_user_sgpr_kernarg_preload_length 0
		.amdhsa_user_sgpr_kernarg_preload_offset 0
		.amdhsa_user_sgpr_private_segment_size 0
		.amdhsa_uses_dynamic_stack 0
		.amdhsa_enable_private_segment 0
		.amdhsa_system_sgpr_workgroup_id_x 1
		.amdhsa_system_sgpr_workgroup_id_y 0
		.amdhsa_system_sgpr_workgroup_id_z 0
		.amdhsa_system_sgpr_workgroup_info 0
		.amdhsa_system_vgpr_workitem_id 2
		.amdhsa_next_free_vgpr 256
		.amdhsa_next_free_sgpr 102
		.amdhsa_accum_offset 256
		.amdhsa_reserve_vcc 1
		.amdhsa_float_round_mode_32 0
		.amdhsa_float_round_mode_16_64 0
		.amdhsa_float_denorm_mode_32 3
		.amdhsa_float_denorm_mode_16_64 3
		.amdhsa_dx10_clamp 1
		.amdhsa_ieee_mode 1
		.amdhsa_fp16_overflow 0
		.amdhsa_tg_split 0
		.amdhsa_exception_fp_ieee_invalid_op 0
		.amdhsa_exception_fp_denorm_src 0
		.amdhsa_exception_fp_ieee_div_zero 0
		.amdhsa_exception_fp_ieee_overflow 0
		.amdhsa_exception_fp_ieee_underflow 0
		.amdhsa_exception_fp_ieee_inexact 0
		.amdhsa_exception_int_div_zero 0
	.end_amdhsa_kernel

amdhsa.kernels:
  - .agpr_count:     0
    .args:
      - .offset:         0
        .size:           328
        .value_kind:     by_value
      - .offset:         328
        .size:           4
        .value_kind:     hidden_block_count_x
      - .offset:         332
        .size:           4
        .value_kind:     hidden_block_count_y
      - .offset:         336
        .size:           4
        .value_kind:     hidden_block_count_z
      - .offset:         340
        .size:           2
        .value_kind:     hidden_group_size_x
      - .offset:         342
        .size:           2
        .value_kind:     hidden_group_size_y
      - .offset:         344
        .size:           2
        .value_kind:     hidden_group_size_z
      - .offset:         346
        .size:           2
        .value_kind:     hidden_remainder_x
      - .offset:         348
        .size:           2
        .value_kind:     hidden_remainder_y
      - .offset:         350
        .size:           2
        .value_kind:     hidden_remainder_z
      - .offset:         368
        .size:           8
        .value_kind:     hidden_global_offset_x
      - .offset:         376
        .size:           8
        .value_kind:     hidden_global_offset_y
      - .offset:         384
        .size:           8
        .value_kind:     hidden_global_offset_z
      - .offset:         392
        .size:           2
        .value_kind:     hidden_grid_dims
      - .offset:         416
        .size:           8
        .value_kind:     hidden_multigrid_sync_arg
    .group_segment_fixed_size: 148752
    .kernarg_segment_align: 8
    .kernarg_segment_size: 584
    .language:       OpenCL C
    .language_version:
      - 2
      - 0
    .max_flat_workgroup_size: 512
    .name:           _Z4mega6Params
    .private_segment_fixed_size: 0
    .sgpr_count:     108
    .sgpr_spill_count: 124
    .symbol:         _Z4mega6Params.kd
    .uniform_work_group_size: 1
    .uses_dynamic_stack: false
    .vgpr_count:     256
    .vgpr_spill_count: 0
    .wavefront_size: 64
